# V26 plus critical-path priority 2 for workgroups 0-31 that carry the extra sample-row task in phases 6 and 7
# baseline (speedup 1.0000x reference)
; DI int TIDX() { int t = __builtin_amdgcn_workitem_id_x(); asm volatile("" : "+v"(t)); return t; }
; DI void phase6(const Params& p, int l, unsigned char* smem) {
;   const u16* H = (const u16*)(p.ws + W_H); const u16* WinT = (const u16*)(p.ws + W_WINT);
;   const u16* YG = (const u16*)(p.ws + W_YG); u16* MG = (u16*)(p.ws + W_MG);
;   for (int t0 = blockIdx.x; t0 < 32 + 128 * 8; t0 += gridDim.x) {
;     if (t0 < 32) {
;       const int lane = TIDX() & 63, wave = TIDX() >> 6, r = lane & 31, hl = lane >> 5;
;       const int unit = t0 * 4 + wave, row0 = NP + (unit & 3) * 32, n0 = (unit >> 2) * 32;
.Lprio6_skip:
	s_cmpk_gt_u32 s36, 31
	s_cbranch_scc1 .Lprio6_crit
	s_setprio 2

; DI int TIDX() { int t = __builtin_amdgcn_workitem_id_x(); asm volatile("" : "+v"(t)); return t; }
; DI void phase7(const Params& p, int l, unsigned char* smem) {
;   const u16* MG = (const u16*)(p.ws + W_MG);
;   const float* mod = (const float*)(p.ws + W_MOD);
;   const int ntile = 32 + 128 * 8, nextra = (l + 1 < NL) ? WIN_TT + SMALLW_TT : 0;
;   for (int t0 = blockIdx.x; t0 < ntile + nextra; t0 += gridDim.x) {
;     if (t0 >= ntile + WIN_TT) { smallw_transpose_task(p, l + 1, t0 - ntile - WIN_TT, smem); continue; }
;     if (t0 >= ntile) { win_transpose_task(p, l + 1, t0 - ntile, smem); continue; }
;     if (t0 < 32) {
;       const int lane = TIDX() & 63, wave = TIDX() >> 6, r = lane & 31, hl = lane >> 5;
;       const int unit = t0 * 4 + wave, row0 = NP + (unit & 3) * 32, n0 = (unit >> 2) * 32;
.Lprio7_skip:
	s_cmpk_gt_u32 s95, 31
	s_cbranch_scc1 .Lprio7_crit
	s_setprio 2
